# conv d-loop: B-fragment zeroing skipped by a scalar branch when every lane is in range
# speedup vs baseline: 1.0021x; 1.0002x over previous
.Lconv_dloop_0:
	v_add_u32_e32 v38, 0xffffff80, v38
	v_add_u32_e32 v39, -1, v39
	v_subrev_u32_e32 v40, 64, v40
	v_add_u32_e32 v37, 1, v37
	v_max_i32_e32 v140, 0, v38
	v_cmp_lt_i32_e64 s[38:39], -1, v39
	v_cmp_gt_i32_e64 s[100:101], s80, v39
	s_nop 1
	s_and_b64 s[38:39], s[38:39], s[100:101]
	v_cndmask_b32_e64 v41, 0, v40, s[38:39]
	v_or_b32_e32 v41, v41, v45
	v_lshl_add_u32 v41, v41, 1, v55
	ds_read_b128 v[124:127], v41
	ds_read_b128 v[128:131], v41 offset:32
	ds_read_b128 v[132:135], v41 offset:64
	ds_read_b128 v[136:139], v41 offset:96
	ds_read_b128 v[116:119], v140 offset:64
	ds_read_b128 v[120:123], v140 offset:96
	s_waitcnt lgkmcnt(6)
	s_xor_b64 s[100:101], s[36:37], exec
	s_cbranch_scc0 .Lconv_dskip_0_0
	v_cndmask_b32_e64 v92, 0, v92, s[36:37]
	v_cndmask_b32_e64 v93, 0, v93, s[36:37]
	v_cndmask_b32_e64 v94, 0, v94, s[36:37]
	v_cndmask_b32_e64 v95, 0, v95, s[36:37]
	v_cndmask_b32_e64 v96, 0, v96, s[36:37]
	v_cndmask_b32_e64 v97, 0, v97, s[36:37]
	v_cndmask_b32_e64 v98, 0, v98, s[36:37]
	v_cndmask_b32_e64 v99, 0, v99, s[36:37]
	v_cndmask_b32_e64 v100, 0, v100, s[36:37]
	v_cndmask_b32_e64 v101, 0, v101, s[36:37]
	v_cndmask_b32_e64 v102, 0, v102, s[36:37]
	v_cndmask_b32_e64 v103, 0, v103, s[36:37]
	v_cndmask_b32_e64 v104, 0, v104, s[36:37]
	v_cndmask_b32_e64 v105, 0, v105, s[36:37]
	v_cndmask_b32_e64 v106, 0, v106, s[36:37]
	v_cndmask_b32_e64 v107, 0, v107, s[36:37]
.Lconv_dskip_0_0:
	v_mfma_f32_32x32x16_bf16 v[16:31], v[108:111], v[100:103], v[16:31]
	v_mfma_f32_32x32x16_bf16 v[0:15], v[76:79], v[92:95], v[0:15]
	ds_read_b128 v[108:111], v140
	v_mfma_f32_32x32x16_bf16 v[16:31], v[112:115], v[104:107], v[16:31]
	v_mfma_f32_32x32x16_bf16 v[0:15], v[80:83], v[96:99], v[0:15]
	ds_read_b128 v[112:115], v140 offset:32
	v_mfma_f32_32x32x16_bf16 v[16:31], v[84:87], v[92:95], v[16:31]
	v_mfma_f32_32x32x16_bf16 v[0:15], v[84:87], v[100:103], v[0:15]
	v_mfma_f32_32x32x16_bf16 v[16:31], v[88:91], v[96:99], v[16:31]
	v_mfma_f32_32x32x16_bf16 v[0:15], v[88:91], v[104:107], v[0:15]
	v_cmp_ge_i32_e64 s[100:101], v37, v36
	s_nop 1
	s_or_b64 s[50:51], s[100:101], s[50:51]
	s_andn2_b64 exec, exec, s[50:51]
	s_cbranch_execz .Lconv_ddone_0
	v_add_u32_e32 v38, 0xffffff80, v38
	v_add_u32_e32 v39, -1, v39
	v_subrev_u32_e32 v40, 64, v40
	v_add_u32_e32 v37, 1, v37
	v_max_i32_e32 v140, 0, v38
	v_cmp_lt_i32_e64 s[36:37], -1, v39
	v_cmp_gt_i32_e64 s[100:101], s80, v39
	s_nop 1
	s_and_b64 s[36:37], s[36:37], s[100:101]
	v_cndmask_b32_e64 v41, 0, v40, s[36:37]
	v_or_b32_e32 v41, v41, v45
	v_lshl_add_u32 v41, v41, 1, v55
	ds_read_b128 v[92:95], v41
	ds_read_b128 v[96:99], v41 offset:32
	ds_read_b128 v[100:103], v41 offset:64
	ds_read_b128 v[104:107], v41 offset:96
	ds_read_b128 v[84:87], v140 offset:64
	ds_read_b128 v[88:91], v140 offset:96
	s_waitcnt lgkmcnt(6)
	s_xor_b64 s[100:101], s[38:39], exec
	s_cbranch_scc0 .Lconv_dskip_0_1
	v_cndmask_b32_e64 v124, 0, v124, s[38:39]
	v_cndmask_b32_e64 v125, 0, v125, s[38:39]
	v_cndmask_b32_e64 v126, 0, v126, s[38:39]
	v_cndmask_b32_e64 v127, 0, v127, s[38:39]
	v_cndmask_b32_e64 v128, 0, v128, s[38:39]
	v_cndmask_b32_e64 v129, 0, v129, s[38:39]
	v_cndmask_b32_e64 v130, 0, v130, s[38:39]
	v_cndmask_b32_e64 v131, 0, v131, s[38:39]
	v_cndmask_b32_e64 v132, 0, v132, s[38:39]
	v_cndmask_b32_e64 v133, 0, v133, s[38:39]
	v_cndmask_b32_e64 v134, 0, v134, s[38:39]
	v_cndmask_b32_e64 v135, 0, v135, s[38:39]
	v_cndmask_b32_e64 v136, 0, v136, s[38:39]
	v_cndmask_b32_e64 v137, 0, v137, s[38:39]
	v_cndmask_b32_e64 v138, 0, v138, s[38:39]
	v_cndmask_b32_e64 v139, 0, v139, s[38:39]
.Lconv_dskip_0_1:
	v_mfma_f32_32x32x16_bf16 v[16:31], v[76:79], v[132:135], v[16:31]
	v_mfma_f32_32x32x16_bf16 v[0:15], v[108:111], v[124:127], v[0:15]
	ds_read_b128 v[76:79], v140
	v_mfma_f32_32x32x16_bf16 v[16:31], v[80:83], v[136:139], v[16:31]
	v_mfma_f32_32x32x16_bf16 v[0:15], v[112:115], v[128:131], v[0:15]
	ds_read_b128 v[80:83], v140 offset:32
	v_mfma_f32_32x32x16_bf16 v[16:31], v[116:119], v[124:127], v[16:31]
	v_mfma_f32_32x32x16_bf16 v[0:15], v[116:119], v[132:135], v[0:15]
	v_mfma_f32_32x32x16_bf16 v[16:31], v[120:123], v[128:131], v[16:31]
	v_mfma_f32_32x32x16_bf16 v[0:15], v[120:123], v[136:139], v[0:15]
	v_cmp_ge_i32_e64 s[100:101], v37, v36
	s_nop 1
	s_or_b64 s[50:51], s[100:101], s[50:51]
	s_andn2_b64 exec, exec, s[50:51]
	s_cbranch_execnz .Lconv_dloop_0

.Lconv_dloop_1:
	v_add_u32_e32 v40, 0xffffff80, v40
	v_add_u32_e32 v41, -1, v41
	v_subrev_u32_e32 v42, 64, v42
	v_add_u32_e32 v39, 1, v39
	v_max_i32_e32 v140, 0, v40
	v_cmp_lt_i32_e64 s[36:37], -1, v41
	v_cmp_gt_i32_e64 s[100:101], s65, v41
	s_nop 1
	s_and_b64 s[36:37], s[36:37], s[100:101]
	v_cndmask_b32_e64 v43, 0, v42, s[36:37]
	v_or_b32_e32 v43, v43, v47
	v_lshl_add_u32 v43, v43, 1, v57
	ds_read_b128 v[124:127], v43
	ds_read_b128 v[128:131], v43 offset:32
	ds_read_b128 v[132:135], v43 offset:64
	ds_read_b128 v[136:139], v43 offset:96
	ds_read_b128 v[116:119], v140 offset:64
	ds_read_b128 v[120:123], v140 offset:96
	s_waitcnt lgkmcnt(6)
	s_xor_b64 s[100:101], s[34:35], exec
	s_cbranch_scc0 .Lconv_dskip_1_0
	v_cndmask_b32_e64 v92, 0, v92, s[34:35]
	v_cndmask_b32_e64 v93, 0, v93, s[34:35]
	v_cndmask_b32_e64 v94, 0, v94, s[34:35]
	v_cndmask_b32_e64 v95, 0, v95, s[34:35]
	v_cndmask_b32_e64 v96, 0, v96, s[34:35]
	v_cndmask_b32_e64 v97, 0, v97, s[34:35]
	v_cndmask_b32_e64 v98, 0, v98, s[34:35]
	v_cndmask_b32_e64 v99, 0, v99, s[34:35]
	v_cndmask_b32_e64 v100, 0, v100, s[34:35]
	v_cndmask_b32_e64 v101, 0, v101, s[34:35]
	v_cndmask_b32_e64 v102, 0, v102, s[34:35]
	v_cndmask_b32_e64 v103, 0, v103, s[34:35]
	v_cndmask_b32_e64 v104, 0, v104, s[34:35]
	v_cndmask_b32_e64 v105, 0, v105, s[34:35]
	v_cndmask_b32_e64 v106, 0, v106, s[34:35]
	v_cndmask_b32_e64 v107, 0, v107, s[34:35]
.Lconv_dskip_1_0:
	v_mfma_f32_32x32x16_bf16 v[16:31], v[108:111], v[100:103], v[16:31]
	v_mfma_f32_32x32x16_bf16 v[0:15], v[76:79], v[92:95], v[0:15]
	ds_read_b128 v[108:111], v140
	v_mfma_f32_32x32x16_bf16 v[16:31], v[112:115], v[104:107], v[16:31]
	v_mfma_f32_32x32x16_bf16 v[0:15], v[80:83], v[96:99], v[0:15]
	ds_read_b128 v[112:115], v140 offset:32
	v_mfma_f32_32x32x16_bf16 v[16:31], v[84:87], v[92:95], v[16:31]
	v_mfma_f32_32x32x16_bf16 v[0:15], v[84:87], v[100:103], v[0:15]
	v_mfma_f32_32x32x16_bf16 v[16:31], v[88:91], v[96:99], v[16:31]
	v_mfma_f32_32x32x16_bf16 v[0:15], v[88:91], v[104:107], v[0:15]
	v_cmp_ge_i32_e64 s[100:101], v39, v38
	s_nop 1
	s_or_b64 s[46:47], s[100:101], s[46:47]
	s_andn2_b64 exec, exec, s[46:47]
	s_cbranch_execz .Lconv_ddone_1
	v_add_u32_e32 v40, 0xffffff80, v40
	v_add_u32_e32 v41, -1, v41
	v_subrev_u32_e32 v42, 64, v42
	v_add_u32_e32 v39, 1, v39
	v_max_i32_e32 v140, 0, v40
	v_cmp_lt_i32_e64 s[34:35], -1, v41
	v_cmp_gt_i32_e64 s[100:101], s65, v41
	s_nop 1
	s_and_b64 s[34:35], s[34:35], s[100:101]
	v_cndmask_b32_e64 v43, 0, v42, s[34:35]
	v_or_b32_e32 v43, v43, v47
	v_lshl_add_u32 v43, v43, 1, v57
	ds_read_b128 v[92:95], v43
	ds_read_b128 v[96:99], v43 offset:32
	ds_read_b128 v[100:103], v43 offset:64
	ds_read_b128 v[104:107], v43 offset:96
	ds_read_b128 v[84:87], v140 offset:64
	ds_read_b128 v[88:91], v140 offset:96
	s_waitcnt lgkmcnt(6)
	s_xor_b64 s[100:101], s[36:37], exec
	s_cbranch_scc0 .Lconv_dskip_1_1
	v_cndmask_b32_e64 v124, 0, v124, s[36:37]
	v_cndmask_b32_e64 v125, 0, v125, s[36:37]
	v_cndmask_b32_e64 v126, 0, v126, s[36:37]
	v_cndmask_b32_e64 v127, 0, v127, s[36:37]
	v_cndmask_b32_e64 v128, 0, v128, s[36:37]
	v_cndmask_b32_e64 v129, 0, v129, s[36:37]
	v_cndmask_b32_e64 v130, 0, v130, s[36:37]
	v_cndmask_b32_e64 v131, 0, v131, s[36:37]
	v_cndmask_b32_e64 v132, 0, v132, s[36:37]
	v_cndmask_b32_e64 v133, 0, v133, s[36:37]
	v_cndmask_b32_e64 v134, 0, v134, s[36:37]
	v_cndmask_b32_e64 v135, 0, v135, s[36:37]
	v_cndmask_b32_e64 v136, 0, v136, s[36:37]
	v_cndmask_b32_e64 v137, 0, v137, s[36:37]
	v_cndmask_b32_e64 v138, 0, v138, s[36:37]
	v_cndmask_b32_e64 v139, 0, v139, s[36:37]
.Lconv_dskip_1_1:
	v_mfma_f32_32x32x16_bf16 v[16:31], v[76:79], v[132:135], v[16:31]
	v_mfma_f32_32x32x16_bf16 v[0:15], v[108:111], v[124:127], v[0:15]
	ds_read_b128 v[76:79], v140
	v_mfma_f32_32x32x16_bf16 v[16:31], v[80:83], v[136:139], v[16:31]
	v_mfma_f32_32x32x16_bf16 v[0:15], v[112:115], v[128:131], v[0:15]
	ds_read_b128 v[80:83], v140 offset:32
	v_mfma_f32_32x32x16_bf16 v[16:31], v[116:119], v[124:127], v[16:31]
	v_mfma_f32_32x32x16_bf16 v[0:15], v[116:119], v[132:135], v[0:15]
	v_mfma_f32_32x32x16_bf16 v[16:31], v[120:123], v[128:131], v[16:31]
	v_mfma_f32_32x32x16_bf16 v[0:15], v[120:123], v[136:139], v[0:15]
	v_cmp_ge_i32_e64 s[100:101], v39, v38
	s_nop 1
	s_or_b64 s[46:47], s[100:101], s[46:47]
	s_andn2_b64 exec, exec, s[46:47]
	s_cbranch_execnz .Lconv_dloop_1
